# grid barrier spin loops poll without s_sleep
# speedup vs baseline: 1.0034x; 1.0034x over previous
.LBB0_116:
	global_load_dword v16, v17, s[4:5] sc1
	s_waitcnt lgkmcnt(0)
	global_load_dword v0, v17, s[6:7] sc1
	global_load_dword v1, v17, s[8:9] sc1
	global_load_dword v2, v17, s[10:11] sc1
	global_load_dword v3, v17, s[12:13] sc1
	global_load_dword v4, v17, s[14:15] sc1
	global_load_dword v5, v17, s[16:17] sc1
	global_load_dword v6, v17, s[18:19] sc1
	global_load_dword v7, v17, s[20:21] sc1
	global_load_dword v9, v17, s[22:23] sc1
	global_load_dword v10, v17, s[24:25] sc1
	global_load_dword v11, v17, s[26:27] sc1
	global_load_dword v12, v17, s[28:29] sc1
	global_load_dword v13, v17, s[30:31] sc1
	global_load_dword v14, v17, s[34:35] sc1
	global_load_dword v15, v17, s[36:37] sc1
	s_mov_b64 s[38:39], -1
	s_mov_b64 s[40:41], -1
	s_waitcnt vmcnt(14)
	v_add_u32_e32 v18, v0, v16
	s_waitcnt vmcnt(13)
	v_add_u32_e32 v18, v18, v1
	s_waitcnt vmcnt(12)
	v_add_u32_e32 v18, v18, v2
	s_waitcnt vmcnt(11)
	v_add_u32_e32 v18, v18, v3
	s_waitcnt vmcnt(10)
	v_add_u32_e32 v18, v18, v4
	s_waitcnt vmcnt(9)
	v_add_u32_e32 v18, v18, v5
	s_waitcnt vmcnt(8)
	v_add_u32_e32 v18, v18, v6
	s_waitcnt vmcnt(7)
	v_add_u32_e32 v18, v18, v7
	s_waitcnt vmcnt(6)
	v_add_u32_e32 v18, v18, v9
	s_waitcnt vmcnt(5)
	v_add_u32_e32 v18, v18, v10
	s_waitcnt vmcnt(4)
	v_add_u32_e32 v18, v18, v11
	s_waitcnt vmcnt(3)
	v_add_u32_e32 v18, v18, v12
	s_waitcnt vmcnt(2)
	v_add_u32_e32 v18, v18, v13
	s_waitcnt vmcnt(1)
	v_add_u32_e32 v18, v18, v14
	s_waitcnt vmcnt(0)
	v_add_u32_e32 v18, v18, v15
	v_cmp_eq_u32_e32 vcc, s46, v18
	s_cbranch_vccnz .LBB0_115
	s_and_b32 s38, s47, 0xff
	s_cmp_eq_u32 s38, 0
	s_mov_b64 s[38:39], -1
	s_mov_b64 s[42:43], -1
	s_cbranch_scc1 .LBB0_120
	s_and_b64 vcc, exec, s[42:43]
	s_cbranch_vccz .LBB0_115

.LBB0_134:
	s_and_b32 s18, s22, 0xff
	s_mov_b64 s[16:17], -1
	s_cmp_lg_u32 s18, 0
	s_mov_b64 s[20:21], -1
	s_cbranch_scc0 .LBB0_137
	s_and_b64 vcc, exec, s[20:21]
	s_cbranch_vccz .LBB0_133

.LBB0_151:
	s_and_b32 s18, s24, 0xff
	s_cmp_lg_u32 s18, 0
	s_mov_b64 s[20:21], -1
	s_cbranch_scc0 .LBB0_154
	s_mov_b64 s[22:23], -1
	s_and_b64 vcc, exec, s[20:21]
	s_cbranch_vccz .LBB0_150

.LBB0_233:
	v_readlane_b32 s2, v250, 53
	v_readlane_b32 s3, v250, 54
	v_readlane_b32 s4, v250, 50
	s_nop 3
	global_load_dword v0, v1, s[2:3] sc1
	v_readlane_b32 s2, v250, 55
	v_readlane_b32 s3, v250, 56
	s_waitcnt lgkmcnt(0)
	s_nop 3
	global_load_dword v2, v1, s[2:3] sc1
	v_readlane_b32 s2, v250, 57
	v_readlane_b32 s3, v250, 58
	s_waitcnt vmcnt(0)
	v_add_u32_e32 v17, v2, v0
	s_nop 2
	global_load_dword v3, v1, s[2:3] sc1
	v_readlane_b32 s2, v250, 59
	v_readlane_b32 s3, v250, 60
	s_waitcnt vmcnt(0)
	v_add_u32_e32 v17, v17, v3
	s_nop 2
	global_load_dword v4, v1, s[2:3] sc1
	v_readlane_b32 s2, v250, 61
	v_readlane_b32 s3, v250, 62
	s_waitcnt vmcnt(0)
	v_add_u32_e32 v17, v17, v4
	s_nop 2
	global_load_dword v5, v1, s[2:3] sc1
	v_readlane_b32 s2, v250, 63
	v_readlane_b32 s3, v252, 0
	s_waitcnt vmcnt(0)
	v_add_u32_e32 v17, v17, v5
	s_nop 2
	global_load_dword v6, v1, s[2:3] sc1
	v_readlane_b32 s2, v252, 1
	v_readlane_b32 s3, v252, 2
	s_waitcnt vmcnt(0)
	v_add_u32_e32 v17, v17, v6
	s_nop 2
	global_load_dword v7, v1, s[2:3] sc1
	v_readlane_b32 s2, v252, 3
	v_readlane_b32 s3, v252, 4
	s_waitcnt vmcnt(0)
	v_add_u32_e32 v17, v17, v7
	s_nop 2
	global_load_dword v8, v1, s[2:3] sc1
	v_readlane_b32 s2, v252, 5
	v_readlane_b32 s3, v252, 6
	s_waitcnt vmcnt(0)
	v_add_u32_e32 v17, v17, v8
	s_nop 2
	global_load_dword v9, v1, s[2:3] sc1
	v_readlane_b32 s2, v252, 7
	v_readlane_b32 s3, v252, 8
	s_waitcnt vmcnt(0)
	v_add_u32_e32 v17, v17, v9
	s_nop 2
	global_load_dword v10, v1, s[2:3] sc1
	v_readlane_b32 s2, v252, 9
	v_readlane_b32 s3, v252, 10
	s_waitcnt vmcnt(0)
	v_add_u32_e32 v17, v17, v10
	s_nop 2
	global_load_dword v11, v1, s[2:3] sc1
	v_readlane_b32 s2, v252, 11
	v_readlane_b32 s3, v252, 12
	s_waitcnt vmcnt(0)
	v_add_u32_e32 v17, v17, v11
	s_nop 2
	global_load_dword v12, v1, s[2:3] sc1
	v_readlane_b32 s2, v252, 13
	v_readlane_b32 s3, v252, 14
	s_waitcnt vmcnt(0)
	v_add_u32_e32 v17, v17, v12
	s_nop 2
	global_load_dword v13, v1, s[2:3] sc1
	v_readlane_b32 s2, v252, 15
	v_readlane_b32 s3, v252, 16
	s_waitcnt vmcnt(0)
	v_add_u32_e32 v17, v17, v13
	s_nop 2
	global_load_dword v14, v1, s[2:3] sc1
	v_readlane_b32 s2, v252, 17
	v_readlane_b32 s3, v252, 18
	s_waitcnt vmcnt(0)
	v_add_u32_e32 v17, v17, v14
	s_nop 2
	global_load_dword v15, v1, s[2:3] sc1
	v_readlane_b32 s2, v252, 19
	v_readlane_b32 s3, v252, 20
	s_waitcnt vmcnt(0)
	v_add_u32_e32 v17, v17, v15
	s_nop 2
	global_load_dword v16, v1, s[2:3] sc1
	s_mov_b64 s[2:3], -1
	s_waitcnt vmcnt(0)
	v_add_u32_e32 v17, v17, v16
	v_cmp_eq_u32_e32 vcc, s4, v17
	s_mov_b64 s[4:5], -1
	s_cbranch_vccnz .LBB0_232
	s_and_b32 s2, s9, 0xff
	s_cmp_eq_u32 s2, 0
	s_mov_b64 s[2:3], -1
	s_mov_b64 s[6:7], -1
	s_cbranch_scc1 .LBB0_237
	s_and_b64 vcc, exec, s[6:7]
	s_cbranch_vccz .LBB0_232

.LBB0_251:
	s_and_b32 s16, s20, 0xff
	s_mov_b64 s[14:15], -1
	s_cmp_lg_u32 s16, 0
	s_mov_b64 s[18:19], -1
	s_cbranch_scc0 .LBB0_254
	s_and_b64 vcc, exec, s[18:19]
	s_cbranch_vccz .LBB0_250

.LBB0_1010:
	s_and_b32 s16, s21, 0xff
	s_mov_b64 s[14:15], -1
	s_cmp_lg_u32 s16, 0
	s_mov_b64 s[18:19], -1
	s_cbranch_scc0 .LBB0_1013
	s_and_b64 vcc, exec, s[18:19]
	s_cbranch_vccz .LBB0_1009

.LBB0_1200:
	s_and_b32 s14, s18, 0xff
	s_mov_b64 s[12:13], -1
	s_cmp_lg_u32 s14, 0
	s_mov_b64 s[16:17], -1
	s_cbranch_scc0 .LBB0_1203
	s_and_b64 vcc, exec, s[16:17]
	s_cbranch_vccz .LBB0_1199
